# bundle + MoBA prep q/k rows staged through LDS for full-line global stores
# speedup vs baseline: 1.0144x; 1.0035x over previous
.LBB0_390:
	s_bfe_u32 s1, s0, 0x40003
	s_and_b32 s8, s36, 0xfffff000
	s_lshl_b32 s35, s1, 8
	s_or_b32 s40, s35, s8
	v_add_u32_e32 v2, s40, v140
	v_ashrrev_i32_e32 v3, 31, v2
	s_and_b32 s34, s0, 7
	v_lshlrev_b64 v[2:3], 11, v[2:3]
	v_lshl_add_u64 v[2:3], s[24:25], 0, v[2:3]
	s_lshl_b32 s20, s34, 7
	v_lshl_add_u64 v[2:3], v[2:3], 0, s[20:21]
	v_lshl_add_u64 v[18:19], v[2:3], 0, v[104:105]
	global_load_dwordx4 v[2:5], v[18:19], off offset:1024
	global_load_dwordx4 v[6:9], v[18:19], off offset:1040
	global_load_dwordx4 v[10:13], v[18:19], off offset:1056
	global_load_dwordx4 v[14:17], v[18:19], off offset:1072
	v_or_b32_sdwa v114, s40, v1 dst_sel:DWORD dst_unused:UNUSED_PAD src0_sel:DWORD src1_sel:BYTE_0
	v_ashrrev_i32_e32 v115, 31, v114
	s_waitcnt vmcnt(0)
	ds_write_b16 v141, v2
	ds_write_b16_d16_hi v141, v2 offset:528
	ds_write_b16 v141, v3 offset:1056
	ds_write_b16_d16_hi v141, v3 offset:1584
	ds_write_b16 v141, v4 offset:2112
	ds_write_b16_d16_hi v141, v4 offset:2640
	ds_write_b16 v141, v5 offset:3168
	ds_write_b16_d16_hi v141, v5 offset:3696
	ds_write_b16 v141, v6 offset:4224
	ds_write_b16_d16_hi v141, v6 offset:4752
	ds_write_b16 v141, v7 offset:5280
	ds_write_b16_d16_hi v141, v7 offset:5808
	ds_write_b16 v141, v8 offset:6336
	ds_write_b16_d16_hi v141, v8 offset:6864
	ds_write_b16 v141, v9 offset:7392
	ds_write_b16_d16_hi v141, v9 offset:7920
	ds_write_b16 v141, v10 offset:8448
	ds_write_b16_d16_hi v141, v10 offset:8976
	ds_write_b16 v141, v11 offset:9504
	ds_write_b16_d16_hi v141, v11 offset:10032
	ds_write_b16 v141, v12 offset:10560
	ds_write_b16_d16_hi v141, v12 offset:11088
	ds_write_b16 v141, v13 offset:11616
	ds_write_b16_d16_hi v141, v13 offset:12144
	ds_write_b16 v141, v14 offset:12672
	ds_write_b16_d16_hi v141, v14 offset:13200
	ds_write_b16 v141, v15 offset:13728
	ds_write_b16_d16_hi v141, v15 offset:14256
	ds_write_b16 v141, v16 offset:14784
	ds_write_b16_d16_hi v141, v16 offset:15312
	ds_write_b16 v141, v17 offset:15840
	ds_write_b16_d16_hi v141, v17 offset:16368
	s_waitcnt lgkmcnt(0)
	s_barrier
	s_and_saveexec_b64 s[8:9], s[2:3]
	s_xor_b64 s[8:9], exec, s[8:9]
	v_lshlrev_b64 v[2:3], 11, v[114:115]
	v_lshl_add_u64 v[2:3], s[98:99], 0, v[2:3]
	s_or_saveexec_b64 s[8:9], s[8:9]
	v_mov_b64_e32 v[4:5], s[22:23]
	v_or_b32_e32 v116, s40, v1
	s_xor_b64 exec, exec, s[8:9]
	v_mov_b64_e32 v[2:3], s[14:15]
	v_mad_i64_i32 v[2:3], s[40:41], v116, s38, v[2:3]
	v_lshl_add_u64 v[2:3], v[2:3], 0, s[26:27]
	v_mov_b64_e32 v[4:5], s[18:19]
	s_or_b64 exec, exec, s[8:9]
	global_load_dwordx2 v[112:113], v[4:5], off
	s_lshl_b32 s8, s34, 6
	s_lshl_b32 s20, s8, 1
	v_lshl_add_u64 v[2:3], v[2:3], 0, s[20:21]
	global_load_dwordx4 v[82:85], v[2:3], off offset:48
	global_load_dwordx4 v[86:89], v[2:3], off offset:32
	global_load_dwordx4 v[90:93], v[2:3], off offset:16
	global_load_dwordx4 v[94:97], v[2:3], off
	global_load_dwordx4 v[66:69], v[2:3], off offset:112
	global_load_dwordx4 v[70:73], v[2:3], off offset:96
	global_load_dwordx4 v[74:77], v[2:3], off offset:80
	global_load_dwordx4 v[78:81], v[2:3], off offset:64
	s_waitcnt vmcnt(8)
	global_load_dwordx4 v[46:49], v[112:113], off offset:48
	global_load_dwordx4 v[54:57], v[112:113], off offset:32
	global_load_dwordx4 v[58:61], v[112:113], off offset:16
	global_load_dwordx4 v[62:65], v[112:113], off
	global_load_dwordx4 v[30:33], v[112:113], off offset:112
	global_load_dwordx4 v[38:41], v[112:113], off offset:96
	global_load_dwordx4 v[42:45], v[112:113], off offset:80
	global_load_dwordx4 v[50:53], v[112:113], off offset:64
	global_load_dwordx4 v[14:17], v[112:113], off offset:176
	global_load_dwordx4 v[22:25], v[112:113], off offset:160
	global_load_dwordx4 v[26:29], v[112:113], off offset:144
	global_load_dwordx4 v[34:37], v[112:113], off offset:128
	global_load_dwordx4 v[2:5], v[112:113], off offset:240
	global_load_dwordx4 v[6:9], v[112:113], off offset:224
	global_load_dwordx4 v[10:13], v[112:113], off offset:208
	global_load_dwordx4 v[18:21], v[112:113], off offset:192
	s_and_saveexec_b64 s[8:9], s[2:3]
	s_xor_b64 s[8:9], exec, s[8:9]
	v_lshlrev_b64 v[112:113], 10, v[114:115]
	v_lshl_add_u64 v[112:113], s[12:13], 0, v[112:113]
	s_andn2_saveexec_b64 s[8:9], s[8:9]
	v_ashrrev_i32_e32 v117, 31, v116
	v_lshlrev_b64 v[112:113], 11, v[116:117]
	v_lshl_add_u64 v[112:113], s[24:25], 0, v[112:113]
	v_lshl_add_u64 v[112:113], v[112:113], 0, s[28:29]
	s_or_b64 exec, exec, s[8:9]
	v_or_b32_sdwa v107, s35, v1 dst_sel:DWORD dst_unused:UNUSED_PAD src0_sel:DWORD src1_sel:BYTE_0
	v_cvt_f64_u32_e32 v[114:115], v107
	v_cvt_f32_u32_e32 v109, v107
	v_mul_f64 v[116:117], v[114:115], s[30:31]
	v_rndne_f64_e32 v[116:117], v[116:117]
	v_fma_f64 v[114:115], v[114:115], s[30:31], -v[116:117]
	v_cvt_f32_f64_e32 v107, v[114:115]
	v_sin_f32_e32 v114, v107
	v_cos_f32_e32 v116, v107
	v_mul_f32_e32 v107, 0x3e4693af, v109
	v_cvt_f64_f32_e32 v[118:119], v107
	v_mul_f64 v[120:121], v[118:119], s[30:31]
	v_rndne_f64_e32 v[120:121], v[120:121]
	v_fma_f64 v[118:119], v[118:119], s[30:31], -v[120:121]
	s_waitcnt vmcnt(21)
	v_lshlrev_b32_e32 v122, 16, v90
	v_and_b32_e32 v123, 0xffff0000, v90
	v_mul_f32_e32 v90, 0x3d1a08c8, v109
	v_cvt_f32_f64_e32 v107, v[118:119]
	v_cvt_f64_f32_e32 v[118:119], v90
	v_mul_f64 v[120:121], v[118:119], s[30:31]
	v_rndne_f64_e32 v[120:121], v[120:121]
	v_fma_f64 v[118:119], v[118:119], s[30:31], -v[120:121]
	v_cvt_f32_f64_e32 v90, v[118:119]
	v_sin_f32_e32 v118, v90
	v_cos_f32_e32 v120, v90
	v_mul_f32_e32 v90, 0x3beef74e, v109
	v_cvt_f64_f32_e32 v[126:127], v90
	v_mul_f64 v[128:129], v[126:127], s[30:31]
	v_rndne_f64_e32 v[128:129], v[128:129]
	v_fma_f64 v[126:127], v[126:127], s[30:31], -v[128:129]
	v_cvt_f32_f64_e32 v90, v[126:127]
	v_sin_f32_e32 v119, v90
	v_cos_f32_e32 v121, v90
	v_mul_f32_e32 v90, 0x3ab95d22, v109
	v_lshlrev_b32_e32 v126, 16, v91
	v_and_b32_e32 v127, 0xffff0000, v91
	v_cvt_f64_f32_e32 v[90:91], v90
	s_waitcnt vmcnt(20)
	v_lshlrev_b32_e32 v124, 16, v94
	v_and_b32_e32 v125, 0xffff0000, v94
	v_lshlrev_b32_e32 v128, 16, v95
	v_and_b32_e32 v129, 0xffff0000, v95
	v_mul_f64 v[94:95], v[90:91], s[30:31]
	v_rndne_f64_e32 v[94:95], v[94:95]
	v_fma_f64 v[90:91], v[90:91], s[30:31], -v[94:95]
	v_cvt_f32_f64_e32 v91, v[90:91]
	v_sin_f32_e32 v90, v91
	v_cos_f32_e32 v94, v91
	v_mul_f32_e32 v91, 0x398fc8f8, v109
	v_cvt_f64_f32_e32 v[130:131], v91
	v_mul_f64 v[132:133], v[130:131], s[30:31]
	v_rndne_f64_e32 v[132:133], v[132:133]
	v_fma_f64 v[130:131], v[130:131], s[30:31], -v[132:133]
	v_cvt_f32_f64_e32 v95, v[130:131]
	v_lshlrev_b32_e32 v130, 16, v92
	v_and_b32_e32 v131, 0xffff0000, v92
	v_mul_f32_e32 v92, 0x385f10c5, v109
	v_cvt_f64_f32_e32 v[138:139], v92
	v_mul_f64 v[158:159], v[138:139], s[30:31]
	v_rndne_f64_e32 v[158:159], v[158:159]
	v_sin_f32_e32 v115, v107
	v_cos_f32_e32 v117, v107
	v_fma_f64 v[138:139], v[138:139], s[30:31], -v[158:159]
	v_mul_f32_e32 v107, 0x372d07a8, v109
	v_lshlrev_b32_e32 v132, 16, v96
	v_and_b32_e32 v133, 0xffff0000, v96
	v_cvt_f32_f64_e32 v96, v[138:139]
	v_cvt_f64_f32_e32 v[138:139], v107
	v_mul_f64 v[158:159], v[138:139], s[30:31]
	v_pk_mul_f32 v[136:137], v[124:125], v[124:125]
	v_rndne_f64_e32 v[158:159], v[158:159]
	v_pk_mul_f32 v[150:151], v[128:129], v[128:129]
	v_fma_f64 v[158:159], v[138:139], s[30:31], -v[158:159]
	v_lshlrev_b32_e32 v138, 16, v93
	v_and_b32_e32 v139, 0xffff0000, v93
	v_add_f32_e32 v93, v136, v137
	v_add_f32_e32 v93, v150, v93
	v_pk_mul_f32 v[154:155], v[132:133], v[132:133]
	v_add_f32_e32 v93, v151, v93
	v_lshlrev_b32_e32 v160, 16, v97
	v_and_b32_e32 v161, 0xffff0000, v97
	v_add_f32_e32 v93, v154, v93
	v_pk_mul_f32 v[162:163], v[160:161], v[160:161]
	v_add_f32_e32 v93, v155, v93
	v_add_f32_e32 v93, v162, v93
	v_pk_mul_f32 v[134:135], v[122:123], v[122:123]
	v_add_f32_e32 v93, v163, v93
	v_add_f32_e32 v93, v134, v93
	v_pk_mul_f32 v[152:153], v[126:127], v[126:127]
	v_add_f32_e32 v93, v135, v93
	v_add_f32_e32 v93, v152, v93
	v_pk_mul_f32 v[156:157], v[130:131], v[130:131]
	v_add_f32_e32 v93, v153, v93
	v_add_f32_e32 v93, v156, v93
	v_pk_mul_f32 v[164:165], v[138:139], v[138:139]
	v_add_f32_e32 v93, v157, v93
	v_lshlrev_b32_e32 v166, 16, v86
	v_and_b32_e32 v167, 0xffff0000, v86
	v_add_f32_e32 v93, v164, v93
	v_pk_mul_f32 v[168:169], v[166:167], v[166:167]
	v_add_f32_e32 v93, v165, v93
	v_lshlrev_b32_e32 v86, 16, v87
	v_and_b32_e32 v87, 0xffff0000, v87
	v_add_f32_e32 v93, v168, v93
	v_pk_mul_f32 v[170:171], v[86:87], v[86:87]
	v_add_f32_e32 v93, v169, v93
	v_lshlrev_b32_e32 v172, 16, v88
	v_and_b32_e32 v173, 0xffff0000, v88
	v_add_f32_e32 v93, v170, v93
	v_pk_mul_f32 v[174:175], v[172:173], v[172:173]
	v_add_f32_e32 v93, v171, v93
	v_lshlrev_b32_e32 v88, 16, v89
	v_and_b32_e32 v89, 0xffff0000, v89
	v_add_f32_e32 v93, v174, v93
	v_pk_mul_f32 v[176:177], v[88:89], v[88:89]
	v_add_f32_e32 v93, v175, v93
	v_lshlrev_b32_e32 v178, 16, v82
	v_and_b32_e32 v179, 0xffff0000, v82
	v_add_f32_e32 v93, v176, v93
	v_pk_mul_f32 v[180:181], v[178:179], v[178:179]
	v_add_f32_e32 v93, v177, v93
	v_lshlrev_b32_e32 v82, 16, v83
	v_and_b32_e32 v83, 0xffff0000, v83
	v_add_f32_e32 v93, v180, v93
	v_pk_mul_f32 v[182:183], v[82:83], v[82:83]
	v_add_f32_e32 v93, v181, v93
	v_lshlrev_b32_e32 v184, 16, v84
	v_and_b32_e32 v185, 0xffff0000, v84
	v_add_f32_e32 v93, v182, v93
	v_pk_mul_f32 v[186:187], v[184:185], v[184:185]
	v_add_f32_e32 v93, v183, v93
	v_lshlrev_b32_e32 v84, 16, v85
	v_and_b32_e32 v85, 0xffff0000, v85
	v_add_f32_e32 v93, v186, v93
	v_pk_mul_f32 v[188:189], v[84:85], v[84:85]
	v_add_f32_e32 v93, v187, v93
	s_waitcnt vmcnt(16)
	v_lshlrev_b32_e32 v190, 16, v78
	v_and_b32_e32 v191, 0xffff0000, v78
	v_add_f32_e32 v93, v188, v93
	v_pk_mul_f32 v[192:193], v[190:191], v[190:191]
	v_add_f32_e32 v93, v189, v93
	v_lshlrev_b32_e32 v78, 16, v79
	v_and_b32_e32 v79, 0xffff0000, v79
	v_add_f32_e32 v93, v192, v93
	v_pk_mul_f32 v[194:195], v[78:79], v[78:79]
	v_add_f32_e32 v93, v193, v93
	v_lshlrev_b32_e32 v196, 16, v80
	v_and_b32_e32 v197, 0xffff0000, v80
	v_add_f32_e32 v93, v194, v93
	v_pk_mul_f32 v[198:199], v[196:197], v[196:197]
	v_add_f32_e32 v93, v195, v93
	v_lshlrev_b32_e32 v80, 16, v81
	v_and_b32_e32 v81, 0xffff0000, v81
	v_add_f32_e32 v93, v198, v93
	v_pk_mul_f32 v[200:201], v[80:81], v[80:81]
	v_add_f32_e32 v93, v199, v93
	v_lshlrev_b32_e32 v202, 16, v74
	v_and_b32_e32 v203, 0xffff0000, v74
	v_add_f32_e32 v93, v200, v93
	v_pk_mul_f32 v[204:205], v[202:203], v[202:203]
	v_add_f32_e32 v93, v201, v93
	v_lshlrev_b32_e32 v74, 16, v75
	v_and_b32_e32 v75, 0xffff0000, v75
	v_add_f32_e32 v93, v204, v93
	v_pk_mul_f32 v[206:207], v[74:75], v[74:75]
	v_add_f32_e32 v93, v205, v93
	v_lshlrev_b32_e32 v208, 16, v76
	v_and_b32_e32 v209, 0xffff0000, v76
	v_add_f32_e32 v93, v206, v93
	v_pk_mul_f32 v[210:211], v[208:209], v[208:209]
	v_add_f32_e32 v93, v207, v93
	v_lshlrev_b32_e32 v76, 16, v77
	v_and_b32_e32 v77, 0xffff0000, v77
	v_add_f32_e32 v93, v210, v93
	v_pk_mul_f32 v[212:213], v[76:77], v[76:77]
	v_add_f32_e32 v93, v211, v93
	v_lshlrev_b32_e32 v214, 16, v70
	v_and_b32_e32 v215, 0xffff0000, v70
	v_add_f32_e32 v93, v212, v93
	v_pk_mul_f32 v[216:217], v[214:215], v[214:215]
	v_add_f32_e32 v93, v213, v93
	v_lshlrev_b32_e32 v70, 16, v71
	v_and_b32_e32 v71, 0xffff0000, v71
	v_add_f32_e32 v93, v216, v93
	v_pk_mul_f32 v[218:219], v[70:71], v[70:71]
	v_add_f32_e32 v93, v217, v93
	v_lshlrev_b32_e32 v220, 16, v72
	v_and_b32_e32 v221, 0xffff0000, v72
	v_add_f32_e32 v93, v218, v93
	v_pk_mul_f32 v[222:223], v[220:221], v[220:221]
	v_add_f32_e32 v93, v219, v93
	v_lshlrev_b32_e32 v72, 16, v73
	v_and_b32_e32 v73, 0xffff0000, v73
	v_add_f32_e32 v93, v222, v93
	v_pk_mul_f32 v[224:225], v[72:73], v[72:73]
	v_add_f32_e32 v93, v223, v93
	v_lshlrev_b32_e32 v226, 16, v66
	v_and_b32_e32 v227, 0xffff0000, v66
	v_add_f32_e32 v93, v224, v93
	v_pk_mul_f32 v[228:229], v[226:227], v[226:227]
	v_add_f32_e32 v93, v225, v93
	v_lshlrev_b32_e32 v66, 16, v67
	v_and_b32_e32 v67, 0xffff0000, v67
	v_add_f32_e32 v93, v228, v93
	v_pk_mul_f32 v[230:231], v[66:67], v[66:67]
	v_add_f32_e32 v93, v229, v93
	v_lshlrev_b32_e32 v232, 16, v68
	v_and_b32_e32 v233, 0xffff0000, v68
	v_add_f32_e32 v93, v230, v93
	v_pk_mul_f32 v[234:235], v[232:233], v[232:233]
	v_add_f32_e32 v93, v231, v93
	v_lshlrev_b32_e32 v68, 16, v69
	v_and_b32_e32 v69, 0xffff0000, v69
	v_add_f32_e32 v93, v234, v93
	v_pk_mul_f32 v[236:237], v[68:69], v[68:69]
	v_add_f32_e32 v93, v235, v93
	v_add_f32_e32 v93, v236, v93
	v_add_f32_e32 v93, v237, v93
	v_fmamk_f32 v93, v93, 0x3c800000, v144
	v_mul_f32_e32 v97, 0x4b800000, v93
	v_cmp_gt_f32_e64 s[8:9], s39, v93
	v_sin_f32_e32 v91, v95
	v_sin_f32_e32 v92, v96
	v_cndmask_b32_e64 v93, v93, v97, s[8:9]
	v_rsq_f32_e32 v107, v93
	v_cvt_f32_f64_e32 v97, v[158:159]
	v_sin_f32_e32 v93, v97
	v_cos_f32_e32 v95, v95
	v_mul_f32_e32 v109, 0x45800000, v107
	v_cndmask_b32_e64 v134, v107, v109, s[8:9]
	v_pk_mul_f32 v[124:125], v[134:135], v[124:125] op_sel_hi:[0,1]
	s_waitcnt vmcnt(12)
	v_pk_mul_f32 v[62:63], v[62:63], v[124:125]
	v_pk_mul_f32 v[124:125], v[134:135], v[128:129] op_sel_hi:[0,1]
	v_pk_mul_f32 v[64:65], v[64:65], v[124:125]
	v_pk_mul_f32 v[124:125], v[134:135], v[132:133] op_sel_hi:[0,1]
	v_pk_mul_f32 v[58:59], v[58:59], v[124:125]
	v_pk_mul_f32 v[124:125], v[134:135], v[160:161] op_sel_hi:[0,1]
	v_pk_mul_f32 v[124:125], v[60:61], v[124:125]
	v_pk_mul_f32 v[60:61], v[134:135], v[122:123] op_sel_hi:[0,1]
	v_pk_mul_f32 v[54:55], v[54:55], v[60:61]
	v_pk_mul_f32 v[60:61], v[134:135], v[126:127] op_sel_hi:[0,1]
	v_pk_mul_f32 v[60:61], v[56:57], v[60:61]
	v_pk_mul_f32 v[56:57], v[134:135], v[130:131] op_sel_hi:[0,1]
	v_pk_mul_f32 v[122:123], v[46:47], v[56:57]
	v_pk_mul_f32 v[46:47], v[134:135], v[138:139] op_sel_hi:[0,1]
	v_pk_mul_f32 v[126:127], v[48:49], v[46:47]
	v_pk_mul_f32 v[46:47], v[134:135], v[166:167] op_sel_hi:[0,1]
	s_waitcnt vmcnt(8)
	v_pk_mul_f32 v[46:47], v[50:51], v[46:47]
	v_pk_mul_f32 v[50:51], v[134:135], v[172:173] op_sel_hi:[0,1]
	v_pk_mul_f32 v[42:43], v[42:43], v[50:51]
	v_pk_mul_f32 v[50:51], v[134:135], v[88:89] op_sel_hi:[0,1]
	v_pk_mul_f32 v[44:45], v[44:45], v[50:51]
	v_pk_mul_f32 v[50:51], v[134:135], v[178:179] op_sel_hi:[0,1]
	v_pk_mul_f32 v[38:39], v[38:39], v[50:51]
	v_pk_mul_f32 v[50:51], v[134:135], v[82:83] op_sel_hi:[0,1]
	v_pk_mul_f32 v[40:41], v[40:41], v[50:51]
	v_pk_mul_f32 v[50:51], v[134:135], v[184:185] op_sel_hi:[0,1]
	v_pk_mul_f32 v[30:31], v[30:31], v[50:51]
	v_pk_mul_f32 v[50:51], v[134:135], v[84:85] op_sel_hi:[0,1]
	v_pk_mul_f32 v[32:33], v[32:33], v[50:51]
	v_pk_mul_f32 v[50:51], v[134:135], v[190:191] op_sel_hi:[0,1]
	s_waitcnt vmcnt(4)
	v_pk_mul_f32 v[34:35], v[34:35], v[50:51]
	v_pk_mul_f32 v[50:51], v[134:135], v[78:79] op_sel_hi:[0,1]
	v_pk_mul_f32 v[36:37], v[36:37], v[50:51]
	v_pk_mul_f32 v[50:51], v[134:135], v[196:197] op_sel_hi:[0,1]
	v_pk_mul_f32 v[26:27], v[26:27], v[50:51]
	v_pk_mul_f32 v[50:51], v[134:135], v[80:81] op_sel_hi:[0,1]
	v_pk_mul_f32 v[28:29], v[28:29], v[50:51]
	v_pk_mul_f32 v[50:51], v[134:135], v[202:203] op_sel_hi:[0,1]
	v_pk_mul_f32 v[22:23], v[22:23], v[50:51]
	v_pk_mul_f32 v[50:51], v[134:135], v[74:75] op_sel_hi:[0,1]
	v_pk_mul_f32 v[24:25], v[24:25], v[50:51]
	v_pk_mul_f32 v[50:51], v[134:135], v[208:209] op_sel_hi:[0,1]
	v_pk_mul_f32 v[14:15], v[14:15], v[50:51]
	v_pk_mul_f32 v[50:51], v[134:135], v[76:77] op_sel_hi:[0,1]
	v_pk_mul_f32 v[16:17], v[16:17], v[50:51]
	v_pk_mul_f32 v[50:51], v[134:135], v[214:215] op_sel_hi:[0,1]
	s_waitcnt vmcnt(0)
	v_pk_mul_f32 v[18:19], v[18:19], v[50:51]
	v_pk_mul_f32 v[50:51], v[134:135], v[70:71] op_sel_hi:[0,1]
	v_pk_mul_f32 v[20:21], v[20:21], v[50:51]
	v_pk_mul_f32 v[50:51], v[134:135], v[220:221] op_sel_hi:[0,1]
	v_pk_mul_f32 v[10:11], v[10:11], v[50:51]
	v_pk_mul_f32 v[50:51], v[134:135], v[72:73] op_sel_hi:[0,1]
	v_pk_mul_f32 v[12:13], v[12:13], v[50:51]
	v_pk_mul_f32 v[50:51], v[134:135], v[226:227] op_sel_hi:[0,1]
	v_pk_mul_f32 v[6:7], v[6:7], v[50:51]
	v_pk_mul_f32 v[50:51], v[134:135], v[66:67] op_sel_hi:[0,1]
	v_pk_mul_f32 v[8:9], v[8:9], v[50:51]
	v_pk_mul_f32 v[50:51], v[134:135], v[232:233] op_sel_hi:[0,1]
	v_pk_mul_f32 v[2:3], v[2:3], v[50:51]
	v_pk_mul_f32 v[50:51], v[134:135], v[68:69] op_sel_hi:[0,1]
	v_pk_mul_f32 v[48:49], v[134:135], v[86:87] op_sel_hi:[0,1]
	v_pk_mul_f32 v[4:5], v[4:5], v[50:51]
	v_pk_mul_f32 v[50:51], v[114:115], v[54:55]
	v_cos_f32_e32 v96, v96
	v_cos_f32_e32 v97, v97
	v_pk_mul_f32 v[48:49], v[52:53], v[48:49]
	v_pk_fma_f32 v[52:53], v[116:117], v[62:63], v[50:51] neg_lo:[0,0,1] neg_hi:[0,0,1]
	v_pk_mul_f32 v[50:51], v[114:115], v[62:63]
	v_pk_mul_f32 v[62:63], v[92:93], v[126:127]
	v_pk_fma_f32 v[50:51], v[116:117], v[54:55], v[50:51]
	v_pk_mul_f32 v[54:55], v[118:119], v[60:61]
	v_lshl_add_u64 v[70:71], v[112:113], 0, s[20:21]
	v_pk_fma_f32 v[56:57], v[120:121], v[64:65], v[54:55] neg_lo:[0,0,1] neg_hi:[0,0,1]
	v_pk_mul_f32 v[54:55], v[118:119], v[64:65]
	v_pk_fma_f32 v[64:65], v[96:97], v[124:125], v[62:63] neg_lo:[0,0,1] neg_hi:[0,0,1]
	v_pk_fma_f32 v[54:55], v[120:121], v[60:61], v[54:55]
	v_pk_mul_f32 v[60:61], v[90:91], v[122:123]
	v_pk_mul_f32 v[62:63], v[92:93], v[124:125]
	v_pk_fma_f32 v[60:61], v[94:95], v[58:59], v[60:61] neg_lo:[0,0,1] neg_hi:[0,0,1]
	v_pk_mul_f32 v[58:59], v[90:91], v[58:59]
	v_pk_fma_f32 v[62:63], v[96:97], v[126:127], v[62:63]
	v_pk_fma_f32 v[58:59], v[94:95], v[122:123], v[58:59]
	v_readfirstlane_b32 s46, v1
	v_and_b32_e32 v239, 63, v1
	s_lshr_b32 s47, s46, 6
	s_cmpk_gt_u32 s46, 0xff
	s_movk_i32 s44, 0x4000
	s_cselect_b32 s44, 0x2000, s44
	s_mov_b32 s45, 0
	s_mul_i32 s48, s47, 0x2400
	s_add_i32 s48, s48, 0x19000
	s_sub_i32 s49, s47, 4
	s_mul_i32 s49, s49, 0x4100
	s_cmpk_gt_u32 s46, 0xff
	s_cselect_b32 s48, s49, s48
	v_mul_u32_u24_e32 v238, 0x90, v239
	v_lshrrev_b32_e32 v240, 3, v239
	v_and_b32_e32 v241, 7, v239
	v_add_u32_e32 v238, s48, v238
	v_mul_u32_u24_e32 v239, 0x90, v240
	s_lshr_b32 s49, s44, 3
	v_lshl_add_u32 v239, v241, 4, v239
	v_mul_lo_u32 v240, v240, s49
	v_readfirstlane_b32 s42, v70
	v_readfirstlane_b32 s43, v71
	v_add_u32_e32 v239, s48, v239
	v_lshl_add_u32 v240, v241, 4, v240
	v_mov_b32_e32 v241, 0
	s_nop 1
	v_lshl_add_u64 v[240:241], s[42:43], 0, v[240:241]
	v_cvt_pk_bf16_f32 v66, v52, v53
	v_cvt_pk_bf16_f32 v67, v56, v57
	v_cvt_pk_bf16_f32 v68, v60, v61
	v_cvt_pk_bf16_f32 v69, v64, v65
	ds_write_b128 v238, v[66:69]
	s_nop 1
	v_cvt_pk_bf16_f32 v66, v50, v51
	v_cvt_pk_bf16_f32 v67, v54, v55
	v_cvt_pk_bf16_f32 v68, v58, v59
	v_cvt_pk_bf16_f32 v69, v62, v63
	ds_write_b128 v238, v[66:69] offset:16
	s_nop 1
	v_cvt_pk_bf16_f32 v66, v46, v47
	v_cvt_pk_bf16_f32 v67, v48, v49
	v_cvt_pk_bf16_f32 v68, v42, v43
	v_cvt_pk_bf16_f32 v69, v44, v45
	ds_write_b128 v238, v[66:69] offset:32
	s_nop 1
	v_cvt_pk_bf16_f32 v66, v38, v39
	v_cvt_pk_bf16_f32 v67, v40, v41
	v_cvt_pk_bf16_f32 v68, v30, v31
	v_cvt_pk_bf16_f32 v69, v32, v33
	ds_write_b128 v238, v[66:69] offset:48
	s_nop 1
	v_cvt_pk_bf16_f32 v66, v34, v35
	v_cvt_pk_bf16_f32 v67, v36, v37
	v_cvt_pk_bf16_f32 v68, v26, v27
	v_cvt_pk_bf16_f32 v69, v28, v29
	ds_write_b128 v238, v[66:69] offset:64
	s_nop 1
	v_cvt_pk_bf16_f32 v66, v22, v23
	v_cvt_pk_bf16_f32 v67, v24, v25
	v_cvt_pk_bf16_f32 v68, v14, v15
	v_cvt_pk_bf16_f32 v69, v16, v17
	ds_write_b128 v238, v[66:69] offset:80
	s_nop 1
	v_cvt_pk_bf16_f32 v66, v18, v19
	v_cvt_pk_bf16_f32 v67, v20, v21
	v_cvt_pk_bf16_f32 v68, v10, v11
	v_cvt_pk_bf16_f32 v69, v12, v13
	ds_write_b128 v238, v[66:69] offset:96
	s_nop 1
	v_cvt_pk_bf16_f32 v66, v6, v7
	v_cvt_pk_bf16_f32 v67, v8, v9
	v_cvt_pk_bf16_f32 v68, v2, v3
	v_cvt_pk_bf16_f32 v69, v4, v5
	ds_write_b128 v238, v[66:69] offset:112
	s_waitcnt lgkmcnt(0)
	ds_read_b128 v[242:245], v239
	ds_read_b128 v[66:69], v239 offset:1152
	s_waitcnt lgkmcnt(1)
	global_store_dwordx4 v[240:241], v[242:245], off
	v_lshl_add_u64 v[240:241], v[240:241], 0, s[44:45]
	s_nop 1
	ds_read_b128 v[242:245], v239 offset:2304
	s_waitcnt lgkmcnt(1)
	global_store_dwordx4 v[240:241], v[66:69], off
	v_lshl_add_u64 v[240:241], v[240:241], 0, s[44:45]
	s_nop 1
	ds_read_b128 v[66:69], v239 offset:3456
	s_waitcnt lgkmcnt(1)
	global_store_dwordx4 v[240:241], v[242:245], off
	v_lshl_add_u64 v[240:241], v[240:241], 0, s[44:45]
	s_nop 1
	ds_read_b128 v[242:245], v239 offset:4608
	s_waitcnt lgkmcnt(1)
	global_store_dwordx4 v[240:241], v[66:69], off
	v_lshl_add_u64 v[240:241], v[240:241], 0, s[44:45]
	s_nop 1
	ds_read_b128 v[66:69], v239 offset:5760
	s_waitcnt lgkmcnt(1)
	global_store_dwordx4 v[240:241], v[242:245], off
	v_lshl_add_u64 v[240:241], v[240:241], 0, s[44:45]
	s_nop 1
	ds_read_b128 v[242:245], v239 offset:6912
	s_waitcnt lgkmcnt(1)
	global_store_dwordx4 v[240:241], v[66:69], off
	v_lshl_add_u64 v[240:241], v[240:241], 0, s[44:45]
	s_nop 1
	ds_read_b128 v[66:69], v239 offset:8064
	s_waitcnt lgkmcnt(1)
	global_store_dwordx4 v[240:241], v[242:245], off
	v_lshl_add_u64 v[240:241], v[240:241], 0, s[44:45]
	s_waitcnt lgkmcnt(0)
	global_store_dwordx4 v[240:241], v[66:69], off
	s_nop 1
	s_and_saveexec_b64 s[8:9], s[4:5]
	s_cbranch_execz .LBB0_400
	ds_write2_b32 v145, v52, v53 offset1:1
	ds_write2_b32 v145, v56, v57 offset0:2 offset1:3
	ds_write2_b32 v145, v60, v61 offset0:4 offset1:5
	ds_write2_b32 v145, v64, v65 offset0:6 offset1:7
	ds_write2_b32 v145, v50, v51 offset0:8 offset1:9
	ds_write2_b32 v145, v54, v55 offset0:10 offset1:11
	ds_write2_b32 v145, v58, v59 offset0:12 offset1:13
	ds_write2_b32 v145, v62, v63 offset0:14 offset1:15
	ds_write2_b32 v145, v46, v47 offset0:16 offset1:17
	ds_write2_b32 v145, v48, v49 offset0:18 offset1:19
	ds_write2_b32 v145, v42, v43 offset0:20 offset1:21
	ds_write2_b32 v145, v44, v45 offset0:22 offset1:23
	ds_write2_b32 v145, v38, v39 offset0:24 offset1:25
	ds_write2_b32 v145, v40, v41 offset0:26 offset1:27
	ds_write2_b32 v145, v30, v31 offset0:28 offset1:29
	ds_write2_b32 v145, v32, v33 offset0:30 offset1:31
	ds_write2_b32 v145, v34, v35 offset0:32 offset1:33
	ds_write2_b32 v145, v36, v37 offset0:34 offset1:35
	ds_write2_b32 v145, v26, v27 offset0:36 offset1:37
	ds_write2_b32 v145, v28, v29 offset0:38 offset1:39
	ds_write2_b32 v145, v22, v23 offset0:40 offset1:41
	ds_write2_b32 v145, v24, v25 offset0:42 offset1:43
	ds_write2_b32 v145, v14, v15 offset0:44 offset1:45
	ds_write2_b32 v145, v16, v17 offset0:46 offset1:47
	ds_write2_b32 v145, v18, v19 offset0:48 offset1:49
	ds_write2_b32 v145, v20, v21 offset0:50 offset1:51
	ds_write2_b32 v145, v10, v11 offset0:52 offset1:53
	ds_write2_b32 v145, v12, v13 offset0:54 offset1:55
	ds_write2_b32 v145, v6, v7 offset0:56 offset1:57
	ds_write2_b32 v145, v8, v9 offset0:58 offset1:59
	ds_write2_b32 v145, v2, v3 offset0:60 offset1:61
	ds_write2_b32 v145, v4, v5 offset0:62 offset1:63
